# v82 + GEMM1 tile map: U workgroups take 3 W tiles, SG workgroups 1 (balances the sigmoid epilogues)
# baseline (speedup 1.0000x reference)
.LBB0_160:
	s_add_i32 s60, s60, 1
	s_mul_i32 s0, s60, s81
	s_mul_hi_u32 s1, s60, s3
	s_add_i32 s1, s1, s0
	s_mul_i32 s0, s60, s3
	s_add_u32 s18, s0, s96
	s_addc_u32 s19, s1, 0
	v_cmp_gt_i64_e32 vcc, s[18:19], v[148:149]
	v_cmp_lt_i64_e64 s[0:1], s[18:19], v[146:147]
	s_cbranch_vccnz .LBB0_162
	s_ashr_i32 s16, s18, 31
	s_lshr_b32 s16, s16, 29
	s_add_i32 s16, s18, s16
	s_ashr_i32 s17, s16, 3
	s_and_b32 s16, s16, -8
	s_sub_i32 s16, s18, s16
	s_cmp_lt_i32 s16, 0
	s_movk_i32 s18, 0xe1
	s_cselect_b32 s18, s18, 0xe0
	s_mul_i32 s16, s16, s18
	s_add_i32 s16, s16, s17
	s_mul_hi_i32 s17, s16, 0x92492493
	s_add_i32 s17, s17, s16
	s_lshr_b32 s18, s17, 31
	s_ashr_i32 s17, s17, 7
	s_add_i32 s17, s17, s18
	s_lshl_b32 s18, s17, 3
	s_sub_i32 s19, 64, s18
	s_min_i32 s19, s19, 8
	s_abs_i32 s20, s19
	v_cvt_f32_u32_e32 v2, s20
	s_sub_i32 s22, 0, s20
	s_mulk_i32 s17, 0xe0
	s_sub_i32 s17, s16, s17
	v_rcp_iflag_f32_e32 v2, v2
	s_abs_i32 s16, s17
	s_xor_b32 s21, s17, s19
	s_ashr_i32 s21, s21, 31
	v_mul_f32_e32 v2, 0x4f7ffffe, v2
	v_cvt_u32_f32_e32 v2, v2
	s_nop 0
	v_readfirstlane_b32 s23, v2
	s_mul_i32 s22, s22, s23
	s_mul_hi_u32 s22, s23, s22
	s_add_i32 s23, s23, s22
	s_mul_hi_u32 s22, s16, s23
	s_mul_i32 s23, s22, s20
	s_sub_i32 s16, s16, s23
	s_add_i32 s30, s22, 1
	s_sub_i32 s23, s16, s20
	s_cmp_ge_u32 s16, s20
	s_cselect_b32 s22, s30, s22
	s_cselect_b32 s16, s23, s16
	s_add_i32 s23, s22, 1
	s_cmp_ge_u32 s16, s20
	s_cselect_b32 s16, s23, s22
	s_xor_b32 s16, s16, s21
	s_sub_i32 s16, s16, s21
	s_mul_i32 s19, s16, s19
	s_sub_i32 s17, s17, s19
	s_add_i32 s20, s18, s17
	s_cmpk_lg_u32 s3, 0x100
	s_cbranch_scc1 .Lg1_map_keep
	s_lshr_b32 s17, s96, 6
	s_mov_b32 s18, 0x9ac31480
	s_movk_i32 s19, 3
	s_cmp_eq_u32 s17, 1
	s_cselect_b32 s18, 0x60f4a0e1, s18
	s_cselect_b32 s19, 4, s19
	s_cmp_eq_u32 s17, 2
	s_cselect_b32 s18, 0xab492d42, s18
	s_cselect_b32 s19, 5, s19
	s_cmp_eq_u32 s17, 3
	s_cselect_b32 s18, 0xf59c5e63, s18
	s_cselect_b32 s19, 6, s19
	s_mul_i32 s17, s60, 5
	s_lshr_b64 s[18:19], s[18:19], s17
	s_and_b32 s16, s18, 31
.Lg1_map_keep:
.LBB0_162:
	s_ashr_i32 s21, s20, 31
	s_lshl_b64 s[18:19], s[20:21], 19
	s_add_u32 s22, s76, s18
	s_addc_u32 s23, s77, s19
	s_and_b64 s[18:19], s[0:1], exec
	s_cselect_b32 s18, s23, s53
	s_cselect_b32 s19, s22, s52
	s_ashr_i32 s17, s16, 31
	s_lshl_b64 s[30:31], s[16:17], 19
	s_add_u32 s30, s2, s30
	s_addc_u32 s31, s24, s31
	s_and_b64 s[56:57], s[0:1], exec
	s_cselect_b32 s17, s31, s55
	s_cselect_b32 s21, s30, s54
	s_add_u32 s52, s52, 0x40080
	s_addc_u32 s53, s53, 0
	s_add_u32 s90, s54, 0x100
	v_mov_b32_e32 v2, 0
	s_addc_u32 s91, s55, 0
	s_mov_b32 s92, -2
	v_mov_b32_e32 v3, v2
	v_mov_b32_e32 v4, v2
	v_mov_b32_e32 v5, v2
	v_mov_b32_e32 v6, v2
	v_mov_b32_e32 v7, v2
	v_mov_b32_e32 v8, v2
	v_mov_b32_e32 v9, v2
	v_mov_b32_e32 v10, v2
	v_mov_b32_e32 v11, v2
	v_mov_b32_e32 v12, v2
	v_mov_b32_e32 v13, v2
	v_mov_b32_e32 v14, v2
	v_mov_b32_e32 v15, v2
	v_mov_b32_e32 v16, v2
	v_mov_b32_e32 v17, v2
	v_mov_b32_e32 v26, v2
	v_mov_b32_e32 v27, v2
	v_mov_b32_e32 v28, v2
	v_mov_b32_e32 v29, v2
	v_mov_b32_e32 v30, v2
	v_mov_b32_e32 v31, v2
	v_mov_b32_e32 v32, v2
	v_mov_b32_e32 v33, v2
	v_mov_b32_e32 v42, v2
	v_mov_b32_e32 v43, v2
	v_mov_b32_e32 v44, v2
	v_mov_b32_e32 v45, v2
	v_mov_b32_e32 v46, v2
	v_mov_b32_e32 v47, v2
	v_mov_b32_e32 v48, v2
	v_mov_b32_e32 v49, v2
	v_mov_b32_e32 v18, v2
	v_mov_b32_e32 v19, v2
	v_mov_b32_e32 v20, v2
	v_mov_b32_e32 v21, v2
	v_mov_b32_e32 v22, v2
	v_mov_b32_e32 v23, v2
	v_mov_b32_e32 v24, v2
	v_mov_b32_e32 v25, v2
	v_mov_b32_e32 v34, v2
	v_mov_b32_e32 v35, v2
	v_mov_b32_e32 v36, v2
	v_mov_b32_e32 v37, v2
	v_mov_b32_e32 v38, v2
	v_mov_b32_e32 v39, v2
	v_mov_b32_e32 v40, v2
	v_mov_b32_e32 v41, v2
	v_mov_b32_e32 v50, v2
	v_mov_b32_e32 v51, v2
	v_mov_b32_e32 v52, v2
	v_mov_b32_e32 v53, v2
	v_mov_b32_e32 v54, v2
	v_mov_b32_e32 v55, v2
	v_mov_b32_e32 v56, v2
	v_mov_b32_e32 v57, v2
	v_mov_b32_e32 v58, v2
	v_mov_b32_e32 v59, v2
	v_mov_b32_e32 v60, v2
	v_mov_b32_e32 v61, v2
	v_mov_b32_e32 v62, v2
	v_mov_b32_e32 v63, v2
	v_mov_b32_e32 v64, v2
	v_mov_b32_e32 v65, v2
	v_mov_b32_e32 v66, v2
	v_mov_b32_e32 v67, v2
	v_mov_b32_e32 v68, v2
	v_mov_b32_e32 v69, v2
	v_mov_b32_e32 v70, v2
	v_mov_b32_e32 v71, v2
	v_mov_b32_e32 v72, v2
	v_mov_b32_e32 v73, v2
	v_mov_b32_e32 v74, v2
	v_mov_b32_e32 v75, v2
	v_mov_b32_e32 v76, v2
	v_mov_b32_e32 v77, v2
	v_mov_b32_e32 v78, v2
	v_mov_b32_e32 v79, v2
	v_mov_b32_e32 v80, v2
	v_mov_b32_e32 v81, v2
	v_mov_b32_e32 v90, v2
	v_mov_b32_e32 v91, v2
	v_mov_b32_e32 v92, v2
	v_mov_b32_e32 v93, v2
	v_mov_b32_e32 v94, v2
	v_mov_b32_e32 v95, v2
	v_mov_b32_e32 v96, v2
	v_mov_b32_e32 v97, v2
	v_mov_b32_e32 v106, v2
	v_mov_b32_e32 v107, v2
	v_mov_b32_e32 v108, v2
	v_mov_b32_e32 v109, v2
	v_mov_b32_e32 v110, v2
	v_mov_b32_e32 v111, v2
	v_mov_b32_e32 v112, v2
	v_mov_b32_e32 v113, v2
	v_mov_b32_e32 v82, v2
	v_mov_b32_e32 v83, v2
	v_mov_b32_e32 v84, v2
	v_mov_b32_e32 v85, v2
	v_mov_b32_e32 v86, v2
	v_mov_b32_e32 v87, v2
	v_mov_b32_e32 v88, v2
	v_mov_b32_e32 v89, v2
	v_mov_b32_e32 v98, v2
	v_mov_b32_e32 v99, v2
	v_mov_b32_e32 v100, v2
	v_mov_b32_e32 v101, v2
	v_mov_b32_e32 v102, v2
	v_mov_b32_e32 v103, v2
	v_mov_b32_e32 v104, v2
	v_mov_b32_e32 v105, v2
	v_mov_b32_e32 v114, v2
	v_mov_b32_e32 v115, v2
	v_mov_b32_e32 v116, v2
	v_mov_b32_e32 v117, v2
	v_mov_b32_e32 v118, v2
	v_mov_b32_e32 v119, v2
	v_mov_b32_e32 v120, v2
	v_mov_b32_e32 v121, v2
	v_mov_b32_e32 v122, v2
	v_mov_b32_e32 v123, v2
	v_mov_b32_e32 v124, v2
	v_mov_b32_e32 v125, v2
	v_mov_b32_e32 v126, v2
	v_mov_b32_e32 v127, v2
	v_mov_b32_e32 v128, v2
	v_mov_b32_e32 v129, v2
